# v031 plus: strip scale loads issued together (8 serialized round trips per weight strip removed); layer-1 SSM rounds rebalanced 3/6 to 4/5 in phase D
# speedup vs baseline: 1.0318x; 1.0075x over previous
.LBB0_9:
	s_cmpk_gt_i32 s49, 0x37f
	s_mov_b64 s[4:5], -1
	s_cbranch_scc0 .LBB0_27
	s_load_dwordx16 s[8:23], s[0:1], 0x80
	s_add_i32 s4, s42, 0xfffe8000
	s_and_b32 s34, s4, 0x300
	s_add_i32 s4, s44, 0xffffe800
	s_and_b32 s26, s4, 0x3fc0
	v_mov_b32_e32 v39, v194
	s_lshl_b32 s4, s26, 2
	v_lshlrev_b32_e32 v2, 2, v39
	s_waitcnt lgkmcnt(0)
	s_add_u32 s4, s22, s4
	v_and_b32_e32 v40, 60, v2
	s_addc_u32 s5, s23, 0
	v_lshlrev_b32_e32 v34, 2, v40
	v_lshl_add_u64 v[2:3], s[4:5], 0, v[34:35]
	v_ashrrev_i32_e32 v34, 4, v39
	v_add_u32_e32 v6, s34, v34
	v_ashrrev_i32_e32 v7, 31, v6
	v_lshl_add_u64 v[30:31], v[2:3], 0, s[28:29]
	v_lshlrev_b64 v[2:3], 13, v[6:7]
	v_lshl_add_u64 v[2:3], v[30:31], 0, v[2:3]
	s_barrier
	global_load_dwordx4 v[2:5], v[2:3], off
	v_cmp_ne_u32_e64 s[4:5], 1, v38
	s_andn2_b64 vcc, exec, s[54:55]
	s_cbranch_vccnz .LBB0_12
	v_lshl_add_u64 v[6:7], v[6:7], 2, s[52:53]
	global_load_dword v48, v[6:7], off
.LBB0_12:
	v_add_u32_e32 v6, 0x200, v39
	v_ashrrev_i32_e32 v41, 4, v6
	v_add_u32_e32 v10, s34, v41
	v_ashrrev_i32_e32 v11, 31, v10
	v_lshlrev_b64 v[6:7], 13, v[10:11]
	v_lshl_add_u64 v[6:7], v[30:31], 0, v[6:7]
	global_load_dwordx4 v[6:9], v[6:7], off
	s_and_b64 vcc, exec, s[4:5]
	s_cbranch_vccnz .LBB0_14
	v_lshl_add_u64 v[10:11], v[10:11], 2, s[52:53]
	global_load_dword v50, v[10:11], off
.LBB0_14:
	v_add_u32_e32 v10, 0x400, v39
	v_ashrrev_i32_e32 v42, 4, v10
	v_add_u32_e32 v14, s34, v42
	v_ashrrev_i32_e32 v15, 31, v14
	v_lshlrev_b64 v[10:11], 13, v[14:15]
	v_lshl_add_u64 v[10:11], v[30:31], 0, v[10:11]
	global_load_dwordx4 v[10:13], v[10:11], off
	s_and_b64 vcc, exec, s[4:5]
	s_cbranch_vccnz .LBB0_16
	v_lshl_add_u64 v[14:15], v[14:15], 2, s[52:53]
	global_load_dword v52, v[14:15], off
.LBB0_16:
	v_add_u32_e32 v14, 0x600, v39
	v_ashrrev_i32_e32 v43, 4, v14
	v_add_u32_e32 v18, s34, v43
	v_ashrrev_i32_e32 v19, 31, v18
	v_lshlrev_b64 v[14:15], 13, v[18:19]
	v_lshl_add_u64 v[14:15], v[30:31], 0, v[14:15]
	global_load_dwordx4 v[14:17], v[14:15], off
	s_and_b64 vcc, exec, s[4:5]
	s_cbranch_vccnz .LBB0_18
	v_lshl_add_u64 v[18:19], v[18:19], 2, s[52:53]
	global_load_dword v54, v[18:19], off
.LBB0_18:
	v_add_u32_e32 v18, 0x800, v39
	v_ashrrev_i32_e32 v44, 4, v18
	v_add_u32_e32 v22, s34, v44
	v_ashrrev_i32_e32 v23, 31, v22
	v_lshlrev_b64 v[18:19], 13, v[22:23]
	v_lshl_add_u64 v[18:19], v[30:31], 0, v[18:19]
	global_load_dwordx4 v[18:21], v[18:19], off
	s_and_b64 vcc, exec, s[4:5]
	s_cbranch_vccnz .LBB0_20
	v_lshl_add_u64 v[22:23], v[22:23], 2, s[52:53]
	global_load_dword v56, v[22:23], off
.LBB0_20:
	v_add_u32_e32 v22, 0xa00, v39
	v_ashrrev_i32_e32 v45, 4, v22
	v_add_u32_e32 v26, s34, v45
	v_ashrrev_i32_e32 v27, 31, v26
	v_lshlrev_b64 v[22:23], 13, v[26:27]
	v_lshl_add_u64 v[22:23], v[30:31], 0, v[22:23]
	global_load_dwordx4 v[22:25], v[22:23], off
	s_and_b64 vcc, exec, s[4:5]
	s_cbranch_vccnz .LBB0_22
	v_lshl_add_u64 v[26:27], v[26:27], 2, s[52:53]
	global_load_dword v58, v[26:27], off
.LBB0_22:
	v_add_u32_e32 v26, 0xc00, v39
	v_ashrrev_i32_e32 v46, 4, v26
	v_add_u32_e32 v32, s34, v46
	v_ashrrev_i32_e32 v33, 31, v32
	v_lshlrev_b64 v[26:27], 13, v[32:33]
	v_lshl_add_u64 v[26:27], v[30:31], 0, v[26:27]
	global_load_dwordx4 v[26:29], v[26:27], off
	s_and_b64 vcc, exec, s[4:5]
	s_cbranch_vccnz .LBB0_24
	v_lshl_add_u64 v[32:33], v[32:33], 2, s[52:53]
	global_load_dword v60, v[32:33], off
.LBB0_24:
	v_add_u32_e32 v32, 0xe00, v39
	v_ashrrev_i32_e32 v47, 4, v32
	v_add_u32_e32 v36, s34, v47
	v_ashrrev_i32_e32 v37, 31, v36
	v_lshlrev_b64 v[32:33], 13, v[36:37]
	v_lshl_add_u64 v[30:31], v[30:31], 0, v[32:33]
	global_load_dwordx4 v[30:33], v[30:31], off
	s_and_b64 vcc, exec, s[4:5]
	s_cbranch_vccnz .LBB0_26
	v_lshl_add_u64 v[36:37], v[36:37], 2, s[52:53]
	global_load_dword v62, v[36:37], off
	s_waitcnt vmcnt(0)
	v_pk_mul_f32 v[4:5], v[4:5], v[48:49] op_sel_hi:[1,0]
	v_pk_mul_f32 v[2:3], v[2:3], v[48:49] op_sel_hi:[1,0]
	v_pk_mul_f32 v[8:9], v[8:9], v[50:51] op_sel_hi:[1,0]
	v_pk_mul_f32 v[6:7], v[6:7], v[50:51] op_sel_hi:[1,0]
	v_pk_mul_f32 v[12:13], v[12:13], v[52:53] op_sel_hi:[1,0]
	v_pk_mul_f32 v[10:11], v[10:11], v[52:53] op_sel_hi:[1,0]
	v_pk_mul_f32 v[16:17], v[16:17], v[54:55] op_sel_hi:[1,0]
	v_pk_mul_f32 v[14:15], v[14:15], v[54:55] op_sel_hi:[1,0]
	v_pk_mul_f32 v[20:21], v[20:21], v[56:57] op_sel_hi:[1,0]
	v_pk_mul_f32 v[18:19], v[18:19], v[56:57] op_sel_hi:[1,0]
	v_pk_mul_f32 v[24:25], v[24:25], v[58:59] op_sel_hi:[1,0]
	v_pk_mul_f32 v[22:23], v[22:23], v[58:59] op_sel_hi:[1,0]
	v_pk_mul_f32 v[28:29], v[28:29], v[60:61] op_sel_hi:[1,0]
	v_pk_mul_f32 v[26:27], v[26:27], v[60:61] op_sel_hi:[1,0]
	v_pk_mul_f32 v[32:33], v[32:33], v[62:63] op_sel_hi:[1,0]
	v_pk_mul_f32 v[30:31], v[30:31], v[62:63] op_sel_hi:[1,0]

.LBB0_35:
	s_andn2_b64 vcc, exec, s[4:5]
	s_cbranch_vccnz .LBB0_53
	s_load_dwordx16 s[8:23], s[0:1], 0x80
	s_and_b32 s26, s44, 0x3fc0
	v_mov_b32_e32 v39, v194
	s_and_b32 s34, s42, 0x300
	s_lshl_b32 s4, s26, 2
	v_lshlrev_b32_e32 v2, 2, v39
	s_waitcnt lgkmcnt(0)
	s_add_u32 s4, s22, s4
	v_and_b32_e32 v40, 60, v2
	s_addc_u32 s5, s23, 0
	v_lshlrev_b32_e32 v34, 2, v40
	v_lshl_add_u64 v[2:3], s[4:5], 0, v[34:35]
	v_ashrrev_i32_e32 v34, 4, v39
	v_add_u32_e32 v6, s34, v34
	v_ashrrev_i32_e32 v7, 31, v6
	v_lshl_add_u64 v[30:31], v[2:3], 0, s[30:31]
	v_lshlrev_b64 v[2:3], 13, v[6:7]
	v_lshl_add_u64 v[2:3], v[30:31], 0, v[2:3]
	s_barrier
	global_load_dwordx4 v[2:5], v[2:3], off
	v_cmp_ne_u32_e64 s[4:5], 1, v38
	s_andn2_b64 vcc, exec, s[54:55]
	s_cbranch_vccnz .LBB0_38
	v_lshl_add_u64 v[6:7], v[6:7], 2, s[20:21]
	global_load_dword v48, v[6:7], off
.LBB0_38:
	v_add_u32_e32 v6, 0x200, v39
	v_ashrrev_i32_e32 v41, 4, v6
	v_add_u32_e32 v10, s34, v41
	v_ashrrev_i32_e32 v11, 31, v10
	v_lshlrev_b64 v[6:7], 13, v[10:11]
	v_lshl_add_u64 v[6:7], v[30:31], 0, v[6:7]
	global_load_dwordx4 v[6:9], v[6:7], off
	s_and_b64 vcc, exec, s[4:5]
	s_cbranch_vccnz .LBB0_40
	s_load_dwordx16 s[8:23], s[0:1], 0x80
	s_waitcnt lgkmcnt(0)
	v_lshl_add_u64 v[10:11], v[10:11], 2, s[20:21]
	global_load_dword v50, v[10:11], off
.LBB0_40:
	v_add_u32_e32 v10, 0x400, v39
	v_ashrrev_i32_e32 v42, 4, v10
	v_add_u32_e32 v14, s34, v42
	v_ashrrev_i32_e32 v15, 31, v14
	v_lshlrev_b64 v[10:11], 13, v[14:15]
	v_lshl_add_u64 v[10:11], v[30:31], 0, v[10:11]
	global_load_dwordx4 v[10:13], v[10:11], off
	s_and_b64 vcc, exec, s[4:5]
	s_cbranch_vccnz .LBB0_42
	s_load_dwordx16 s[8:23], s[0:1], 0x80
	s_waitcnt lgkmcnt(0)
	v_lshl_add_u64 v[14:15], v[14:15], 2, s[20:21]
	global_load_dword v52, v[14:15], off
.LBB0_42:
	v_add_u32_e32 v14, 0x600, v39
	v_ashrrev_i32_e32 v43, 4, v14
	v_add_u32_e32 v18, s34, v43
	v_ashrrev_i32_e32 v19, 31, v18
	v_lshlrev_b64 v[14:15], 13, v[18:19]
	v_lshl_add_u64 v[14:15], v[30:31], 0, v[14:15]
	global_load_dwordx4 v[14:17], v[14:15], off
	s_and_b64 vcc, exec, s[4:5]
	s_cbranch_vccnz .LBB0_44
	s_load_dwordx16 s[8:23], s[0:1], 0x80
	s_waitcnt lgkmcnt(0)
	v_lshl_add_u64 v[18:19], v[18:19], 2, s[20:21]
	global_load_dword v54, v[18:19], off
.LBB0_44:
	v_add_u32_e32 v18, 0x800, v39
	v_ashrrev_i32_e32 v44, 4, v18
	v_add_u32_e32 v22, s34, v44
	v_ashrrev_i32_e32 v23, 31, v22
	v_lshlrev_b64 v[18:19], 13, v[22:23]
	v_lshl_add_u64 v[18:19], v[30:31], 0, v[18:19]
	global_load_dwordx4 v[18:21], v[18:19], off
	s_and_b64 vcc, exec, s[4:5]
	s_cbranch_vccnz .LBB0_46
	s_load_dwordx16 s[8:23], s[0:1], 0x80
	s_waitcnt lgkmcnt(0)
	v_lshl_add_u64 v[22:23], v[22:23], 2, s[20:21]
	global_load_dword v56, v[22:23], off
.LBB0_46:
	v_add_u32_e32 v22, 0xa00, v39
	v_ashrrev_i32_e32 v45, 4, v22
	v_add_u32_e32 v26, s34, v45
	v_ashrrev_i32_e32 v27, 31, v26
	v_lshlrev_b64 v[22:23], 13, v[26:27]
	v_lshl_add_u64 v[22:23], v[30:31], 0, v[22:23]
	global_load_dwordx4 v[22:25], v[22:23], off
	s_and_b64 vcc, exec, s[4:5]
	s_cbranch_vccnz .LBB0_48
	s_load_dwordx16 s[8:23], s[0:1], 0x80
	s_waitcnt lgkmcnt(0)
	v_lshl_add_u64 v[26:27], v[26:27], 2, s[20:21]
	global_load_dword v58, v[26:27], off
.LBB0_48:
	v_add_u32_e32 v26, 0xc00, v39
	v_ashrrev_i32_e32 v46, 4, v26
	v_add_u32_e32 v32, s34, v46
	v_ashrrev_i32_e32 v33, 31, v32
	v_lshlrev_b64 v[26:27], 13, v[32:33]
	v_lshl_add_u64 v[26:27], v[30:31], 0, v[26:27]
	global_load_dwordx4 v[26:29], v[26:27], off
	s_and_b64 vcc, exec, s[4:5]
	s_cbranch_vccnz .LBB0_50
	s_load_dwordx16 s[8:23], s[0:1], 0x80
	s_waitcnt lgkmcnt(0)
	v_lshl_add_u64 v[32:33], v[32:33], 2, s[20:21]
	global_load_dword v60, v[32:33], off
.LBB0_50:
	v_add_u32_e32 v32, 0xe00, v39
	v_ashrrev_i32_e32 v47, 4, v32
	v_add_u32_e32 v36, s34, v47
	v_ashrrev_i32_e32 v37, 31, v36
	v_lshlrev_b64 v[32:33], 13, v[36:37]
	v_lshl_add_u64 v[30:31], v[30:31], 0, v[32:33]
	global_load_dwordx4 v[30:33], v[30:31], off
	s_and_b64 vcc, exec, s[4:5]
	s_cbranch_vccnz .LBB0_52
	s_load_dwordx16 s[8:23], s[0:1], 0x80
	s_waitcnt lgkmcnt(0)
	v_lshl_add_u64 v[36:37], v[36:37], 2, s[20:21]
	global_load_dword v62, v[36:37], off
	s_waitcnt vmcnt(0)
	v_pk_mul_f32 v[4:5], v[4:5], v[48:49] op_sel_hi:[1,0]
	v_pk_mul_f32 v[2:3], v[2:3], v[48:49] op_sel_hi:[1,0]
	v_pk_mul_f32 v[8:9], v[8:9], v[50:51] op_sel_hi:[1,0]
	v_pk_mul_f32 v[6:7], v[6:7], v[50:51] op_sel_hi:[1,0]
	v_pk_mul_f32 v[12:13], v[12:13], v[52:53] op_sel_hi:[1,0]
	v_pk_mul_f32 v[10:11], v[10:11], v[52:53] op_sel_hi:[1,0]
	v_pk_mul_f32 v[16:17], v[16:17], v[54:55] op_sel_hi:[1,0]
	v_pk_mul_f32 v[14:15], v[14:15], v[54:55] op_sel_hi:[1,0]
	v_pk_mul_f32 v[20:21], v[20:21], v[56:57] op_sel_hi:[1,0]
	v_pk_mul_f32 v[18:19], v[18:19], v[56:57] op_sel_hi:[1,0]
	v_pk_mul_f32 v[24:25], v[24:25], v[58:59] op_sel_hi:[1,0]
	v_pk_mul_f32 v[22:23], v[22:23], v[58:59] op_sel_hi:[1,0]
	v_pk_mul_f32 v[28:29], v[28:29], v[60:61] op_sel_hi:[1,0]
	v_pk_mul_f32 v[26:27], v[26:27], v[60:61] op_sel_hi:[1,0]
	v_pk_mul_f32 v[32:33], v[32:33], v[62:63] op_sel_hi:[1,0]
	v_pk_mul_f32 v[30:31], v[30:31], v[62:63] op_sel_hi:[1,0]

.LBB0_63:
	v_mov_b32_e32 v39, v194
	s_ashr_i32 s5, s4, 31
	s_and_b32 s26, s42, 0x300
	s_lshl_b64 s[4:5], s[4:5], 2
	v_lshlrev_b32_e32 v2, 2, v39
	s_add_u32 s4, s62, s4
	v_and_b32_e32 v40, 60, v2
	s_addc_u32 s5, s63, s5
	v_lshlrev_b32_e32 v34, 2, v40
	v_lshl_add_u64 v[30:31], s[4:5], 0, v[34:35]
	v_ashrrev_i32_e32 v34, 4, v39
	v_add_u32_e32 v6, s26, v34
	v_ashrrev_i32_e32 v7, 31, v6
	v_lshlrev_b64 v[2:3], 15, v[6:7]
	v_lshl_add_u64 v[2:3], v[30:31], 0, v[2:3]
	s_barrier
	global_load_dwordx4 v[2:5], v[2:3], off
	v_cndmask_b32_e64 v8, 0, 1, s[24:25]
	v_cmp_ne_u32_e64 s[4:5], 1, v8
	s_andn2_b64 vcc, exec, s[24:25]
	s_cbranch_vccnz .LBB0_65
	v_lshl_add_u64 v[6:7], v[6:7], 2, s[60:61]
	global_load_dword v68, v[6:7], off
.LBB0_65:
	v_add_u32_e32 v6, 0x200, v39
	v_ashrrev_i32_e32 v41, 4, v6
	v_add_u32_e32 v10, s26, v41
	v_ashrrev_i32_e32 v11, 31, v10
	v_lshlrev_b64 v[6:7], 15, v[10:11]
	v_lshl_add_u64 v[6:7], v[30:31], 0, v[6:7]
	global_load_dwordx4 v[6:9], v[6:7], off
	s_and_b64 vcc, exec, s[4:5]
	s_cbranch_vccnz .LBB0_67
	v_lshl_add_u64 v[10:11], v[10:11], 2, s[60:61]
	global_load_dword v70, v[10:11], off
.LBB0_67:
	v_add_u32_e32 v10, 0x400, v39
	v_ashrrev_i32_e32 v42, 4, v10
	v_add_u32_e32 v14, s26, v42
	v_ashrrev_i32_e32 v15, 31, v14
	v_lshlrev_b64 v[10:11], 15, v[14:15]
	v_lshl_add_u64 v[10:11], v[30:31], 0, v[10:11]
	global_load_dwordx4 v[10:13], v[10:11], off
	s_and_b64 vcc, exec, s[4:5]
	s_cbranch_vccnz .LBB0_69
	v_lshl_add_u64 v[14:15], v[14:15], 2, s[60:61]
	global_load_dword v72, v[14:15], off
.LBB0_69:
	v_add_u32_e32 v14, 0x600, v39
	v_ashrrev_i32_e32 v43, 4, v14
	v_add_u32_e32 v18, s26, v43
	v_ashrrev_i32_e32 v19, 31, v18
	v_lshlrev_b64 v[14:15], 15, v[18:19]
	v_lshl_add_u64 v[14:15], v[30:31], 0, v[14:15]
	global_load_dwordx4 v[14:17], v[14:15], off
	s_and_b64 vcc, exec, s[4:5]
	s_cbranch_vccnz .LBB0_71
	v_lshl_add_u64 v[18:19], v[18:19], 2, s[60:61]
	global_load_dword v74, v[18:19], off
.LBB0_71:
	v_add_u32_e32 v18, 0x800, v39
	v_ashrrev_i32_e32 v44, 4, v18
	v_add_u32_e32 v22, s26, v44
	v_ashrrev_i32_e32 v23, 31, v22
	v_lshlrev_b64 v[18:19], 15, v[22:23]
	v_lshl_add_u64 v[18:19], v[30:31], 0, v[18:19]
	global_load_dwordx4 v[18:21], v[18:19], off
	s_and_b64 vcc, exec, s[4:5]
	s_cbranch_vccnz .LBB0_73
	v_lshl_add_u64 v[22:23], v[22:23], 2, s[60:61]
	global_load_dword v76, v[22:23], off
.LBB0_73:
	v_add_u32_e32 v22, 0xa00, v39
	v_ashrrev_i32_e32 v45, 4, v22
	v_add_u32_e32 v26, s26, v45
	v_ashrrev_i32_e32 v27, 31, v26
	v_lshlrev_b64 v[22:23], 15, v[26:27]
	v_lshl_add_u64 v[22:23], v[30:31], 0, v[22:23]
	global_load_dwordx4 v[22:25], v[22:23], off
	s_and_b64 vcc, exec, s[4:5]
	s_cbranch_vccnz .LBB0_75
	v_lshl_add_u64 v[26:27], v[26:27], 2, s[60:61]
	global_load_dword v78, v[26:27], off
.LBB0_75:
	v_add_u32_e32 v26, 0xc00, v39
	v_ashrrev_i32_e32 v46, 4, v26
	v_add_u32_e32 v32, s26, v46
	v_ashrrev_i32_e32 v33, 31, v32
	v_lshlrev_b64 v[26:27], 15, v[32:33]
	v_lshl_add_u64 v[26:27], v[30:31], 0, v[26:27]
	global_load_dwordx4 v[26:29], v[26:27], off
	s_and_b64 vcc, exec, s[4:5]
	s_cbranch_vccnz .LBB0_77
	v_lshl_add_u64 v[32:33], v[32:33], 2, s[60:61]
	global_load_dword v80, v[32:33], off
.LBB0_77:
	v_add_u32_e32 v32, 0xe00, v39
	v_ashrrev_i32_e32 v47, 4, v32
	v_add_u32_e32 v36, s26, v47
	v_ashrrev_i32_e32 v37, 31, v36
	v_lshlrev_b64 v[32:33], 15, v[36:37]
	v_lshl_add_u64 v[30:31], v[30:31], 0, v[32:33]
	global_load_dwordx4 v[30:33], v[30:31], off
	s_and_b64 vcc, exec, s[4:5]
	s_cbranch_vccnz .LBB0_7
	v_lshl_add_u64 v[36:37], v[36:37], 2, s[60:61]
	global_load_dword v82, v[36:37], off
	s_waitcnt vmcnt(0)
	v_pk_mul_f32 v[4:5], v[4:5], v[68:69] op_sel_hi:[1,0]
	v_pk_mul_f32 v[2:3], v[2:3], v[68:69] op_sel_hi:[1,0]
	v_pk_mul_f32 v[8:9], v[8:9], v[70:71] op_sel_hi:[1,0]
	v_pk_mul_f32 v[6:7], v[6:7], v[70:71] op_sel_hi:[1,0]
	v_pk_mul_f32 v[12:13], v[12:13], v[72:73] op_sel_hi:[1,0]
	v_pk_mul_f32 v[10:11], v[10:11], v[72:73] op_sel_hi:[1,0]
	v_pk_mul_f32 v[16:17], v[16:17], v[74:75] op_sel_hi:[1,0]
	v_pk_mul_f32 v[14:15], v[14:15], v[74:75] op_sel_hi:[1,0]
	v_pk_mul_f32 v[20:21], v[20:21], v[76:77] op_sel_hi:[1,0]
	v_pk_mul_f32 v[18:19], v[18:19], v[76:77] op_sel_hi:[1,0]
	v_pk_mul_f32 v[24:25], v[24:25], v[78:79] op_sel_hi:[1,0]
	v_pk_mul_f32 v[22:23], v[22:23], v[78:79] op_sel_hi:[1,0]
	v_pk_mul_f32 v[28:29], v[28:29], v[80:81] op_sel_hi:[1,0]
	v_pk_mul_f32 v[26:27], v[26:27], v[80:81] op_sel_hi:[1,0]
	v_pk_mul_f32 v[32:33], v[32:33], v[82:83] op_sel_hi:[1,0]
	v_pk_mul_f32 v[30:31], v[30:31], v[82:83] op_sel_hi:[1,0]
	s_branch .LBB0_7

.LBB0_345:
	v_mov_b32_e32 v34, v194
	s_ashr_i32 s1, s0, 31
	s_and_b32 s4, s18, 0x300
	s_lshl_b64 s[0:1], s[0:1], 2
	v_readlane_b32 s5, v235, 16
	v_lshlrev_b32_e32 v0, 2, v34
	v_ashrrev_i32_e32 v36, 4, v34
	s_add_u32 s0, s5, s0
	v_readlane_b32 s5, v235, 17
	v_and_b32_e32 v35, 60, v0
	v_add_u32_e32 v4, s4, v36
	s_addc_u32 s1, s5, s1
	v_lshlrev_b32_e32 v172, 2, v35
	v_ashrrev_i32_e32 v5, 31, v4
	v_lshl_add_u64 v[28:29], s[0:1], 0, v[172:173]
	v_lshlrev_b64 v[0:1], 15, v[4:5]
	v_lshl_add_u64 v[0:1], v[28:29], 0, v[0:1]
	s_barrier
	global_load_dwordx4 v[0:3], v[0:1], off
	v_readlane_b32 s12, v235, 18
	v_readlane_b32 s13, v235, 19
	s_andn2_b64 vcc, exec, s[12:13]
	s_nop 0
	v_cndmask_b32_e64 v6, 0, 1, s[12:13]
	v_cmp_ne_u32_e64 s[0:1], 1, v6
	s_cbranch_vccnz .LBB0_347
	v_lshl_add_u64 v[4:5], v[4:5], 2, s[52:53]
	global_load_dword v60, v[4:5], off
.LBB0_347:
	v_add_u32_e32 v4, 0x200, v34
	v_ashrrev_i32_e32 v37, 4, v4
	v_add_u32_e32 v8, s4, v37
	v_ashrrev_i32_e32 v9, 31, v8
	v_lshlrev_b64 v[4:5], 15, v[8:9]
	v_lshl_add_u64 v[4:5], v[28:29], 0, v[4:5]
	global_load_dwordx4 v[4:7], v[4:5], off
	s_and_b64 vcc, exec, s[0:1]
	s_cbranch_vccnz .LBB0_349
	v_lshl_add_u64 v[8:9], v[8:9], 2, s[52:53]
	global_load_dword v62, v[8:9], off
.LBB0_349:
	v_add_u32_e32 v8, 0x400, v34
	v_ashrrev_i32_e32 v38, 4, v8
	v_add_u32_e32 v12, s4, v38
	v_ashrrev_i32_e32 v13, 31, v12
	v_lshlrev_b64 v[8:9], 15, v[12:13]
	v_lshl_add_u64 v[8:9], v[28:29], 0, v[8:9]
	global_load_dwordx4 v[8:11], v[8:9], off
	s_and_b64 vcc, exec, s[0:1]
	s_cbranch_vccnz .LBB0_351
	v_lshl_add_u64 v[12:13], v[12:13], 2, s[52:53]
	global_load_dword v64, v[12:13], off
.LBB0_351:
	v_add_u32_e32 v12, 0x600, v34
	v_ashrrev_i32_e32 v39, 4, v12
	v_add_u32_e32 v16, s4, v39
	v_ashrrev_i32_e32 v17, 31, v16
	v_lshlrev_b64 v[12:13], 15, v[16:17]
	v_lshl_add_u64 v[12:13], v[28:29], 0, v[12:13]
	global_load_dwordx4 v[12:15], v[12:13], off
	s_and_b64 vcc, exec, s[0:1]
	s_cbranch_vccnz .LBB0_353
	v_lshl_add_u64 v[16:17], v[16:17], 2, s[52:53]
	global_load_dword v66, v[16:17], off
.LBB0_353:
	v_add_u32_e32 v16, 0x800, v34
	v_ashrrev_i32_e32 v40, 4, v16
	v_add_u32_e32 v20, s4, v40
	v_ashrrev_i32_e32 v21, 31, v20
	v_lshlrev_b64 v[16:17], 15, v[20:21]
	v_lshl_add_u64 v[16:17], v[28:29], 0, v[16:17]
	global_load_dwordx4 v[16:19], v[16:17], off
	s_and_b64 vcc, exec, s[0:1]
	s_cbranch_vccnz .LBB0_355
	v_lshl_add_u64 v[20:21], v[20:21], 2, s[52:53]
	global_load_dword v68, v[20:21], off
.LBB0_355:
	v_add_u32_e32 v20, 0xa00, v34
	v_ashrrev_i32_e32 v41, 4, v20
	v_add_u32_e32 v24, s4, v41
	v_ashrrev_i32_e32 v25, 31, v24
	v_lshlrev_b64 v[20:21], 15, v[24:25]
	v_lshl_add_u64 v[20:21], v[28:29], 0, v[20:21]
	global_load_dwordx4 v[20:23], v[20:21], off
	s_and_b64 vcc, exec, s[0:1]
	s_cbranch_vccnz .LBB0_357
	v_lshl_add_u64 v[24:25], v[24:25], 2, s[52:53]
	global_load_dword v70, v[24:25], off
.LBB0_357:
	v_add_u32_e32 v24, 0xc00, v34
	v_ashrrev_i32_e32 v42, 4, v24
	v_add_u32_e32 v30, s4, v42
	v_ashrrev_i32_e32 v31, 31, v30
	v_lshlrev_b64 v[24:25], 15, v[30:31]
	v_lshl_add_u64 v[24:25], v[28:29], 0, v[24:25]
	global_load_dwordx4 v[24:27], v[24:25], off
	s_and_b64 vcc, exec, s[0:1]
	s_cbranch_vccnz .LBB0_359
	v_lshl_add_u64 v[30:31], v[30:31], 2, s[52:53]
	global_load_dword v72, v[30:31], off
.LBB0_359:
	v_add_u32_e32 v30, 0xe00, v34
	v_ashrrev_i32_e32 v43, 4, v30
	v_add_u32_e32 v32, s4, v43
	v_ashrrev_i32_e32 v33, 31, v32
	v_lshlrev_b64 v[30:31], 15, v[32:33]
	v_lshl_add_u64 v[28:29], v[28:29], 0, v[30:31]
	global_load_dwordx4 v[28:31], v[28:29], off
	s_and_b64 vcc, exec, s[0:1]
	s_cbranch_vccnz .LBB0_336
	v_lshl_add_u64 v[32:33], v[32:33], 2, s[52:53]
	global_load_dword v74, v[32:33], off
	s_waitcnt vmcnt(0)
	v_pk_mul_f32 v[2:3], v[2:3], v[60:61] op_sel_hi:[1,0]
	v_pk_mul_f32 v[0:1], v[0:1], v[60:61] op_sel_hi:[1,0]
	v_pk_mul_f32 v[6:7], v[6:7], v[62:63] op_sel_hi:[1,0]
	v_pk_mul_f32 v[4:5], v[4:5], v[62:63] op_sel_hi:[1,0]
	v_pk_mul_f32 v[10:11], v[10:11], v[64:65] op_sel_hi:[1,0]
	v_pk_mul_f32 v[8:9], v[8:9], v[64:65] op_sel_hi:[1,0]
	v_pk_mul_f32 v[14:15], v[14:15], v[66:67] op_sel_hi:[1,0]
	v_pk_mul_f32 v[12:13], v[12:13], v[66:67] op_sel_hi:[1,0]
	v_pk_mul_f32 v[18:19], v[18:19], v[68:69] op_sel_hi:[1,0]
	v_pk_mul_f32 v[16:17], v[16:17], v[68:69] op_sel_hi:[1,0]
	v_pk_mul_f32 v[22:23], v[22:23], v[70:71] op_sel_hi:[1,0]
	v_pk_mul_f32 v[20:21], v[20:21], v[70:71] op_sel_hi:[1,0]
	v_pk_mul_f32 v[26:27], v[26:27], v[72:73] op_sel_hi:[1,0]
	v_pk_mul_f32 v[24:25], v[24:25], v[72:73] op_sel_hi:[1,0]
	v_pk_mul_f32 v[30:31], v[30:31], v[74:75] op_sel_hi:[1,0]
	v_pk_mul_f32 v[28:29], v[28:29], v[74:75] op_sel_hi:[1,0]
	s_branch .LBB0_336

.LBB0_605:
	s_andn2_b64 vcc, exec, s[0:1]
	s_cbranch_vccnz .LBB0_624
	s_lshl_b32 s0, s9, 8
	s_and_b32 s5, s0, 0x300
	s_lshl_b32 s0, s9, 4
	s_and_b32 s4, s0, 0x3fc0
	v_mov_b32_e32 v34, v194
	v_readlane_b32 s12, v237, 4
	s_lshl_b32 s0, s4, 2
	v_readlane_b32 s26, v237, 18
	v_lshlrev_b32_e32 v0, 2, v34
	v_readlane_b32 s27, v237, 19
	s_add_u32 s0, s26, s0
	v_and_b32_e32 v35, 60, v0
	v_ashrrev_i32_e32 v36, 4, v34
	s_addc_u32 s1, s27, 0
	v_lshlrev_b32_e32 v172, 2, v35
	v_add_u32_e32 v4, s5, v36
	v_lshl_add_u64 v[0:1], s[0:1], 0, v[172:173]
	s_mov_b64 s[0:1], 0x7f8000
	v_ashrrev_i32_e32 v5, 31, v4
	v_lshl_add_u64 v[28:29], v[0:1], 0, s[0:1]
	v_lshlrev_b64 v[0:1], 13, v[4:5]
	v_lshl_add_u64 v[0:1], v[28:29], 0, v[0:1]
	s_barrier
	global_load_dwordx4 v[0:3], v[0:1], off
	v_readlane_b32 s6, v235, 53
	v_readlane_b32 s7, v235, 54
	s_andn2_b64 vcc, exec, s[6:7]
	v_readlane_b32 s13, v237, 5
	v_cndmask_b32_e64 v6, 0, 1, s[6:7]
	v_cmp_ne_u32_e64 s[0:1], 1, v6
	v_readlane_b32 s14, v237, 6
	v_readlane_b32 s15, v237, 7
	v_readlane_b32 s16, v237, 8
	v_readlane_b32 s17, v237, 9
	v_readlane_b32 s18, v237, 10
	v_readlane_b32 s19, v237, 11
	v_readlane_b32 s20, v237, 12
	v_readlane_b32 s21, v237, 13
	v_readlane_b32 s22, v237, 14
	v_readlane_b32 s23, v237, 15
	v_readlane_b32 s24, v237, 16
	v_readlane_b32 s25, v237, 17
	s_cbranch_vccnz .LBB0_608
	v_readlane_b32 s6, v235, 51
	v_readlane_b32 s7, v235, 52
	s_nop 1
	v_lshl_add_u64 v[4:5], v[4:5], 2, s[6:7]
	global_load_dword v48, v[4:5], off
	s_branch .LBB0_609

.LBB0_609:
	v_add_u32_e32 v4, 0x200, v34
	v_ashrrev_i32_e32 v37, 4, v4
	v_add_u32_e32 v8, s5, v37
	v_ashrrev_i32_e32 v9, 31, v8
	v_lshlrev_b64 v[4:5], 13, v[8:9]
	v_lshl_add_u64 v[4:5], v[28:29], 0, v[4:5]
	global_load_dwordx4 v[4:7], v[4:5], off
	s_and_b64 vcc, exec, s[0:1]
	s_cbranch_vccnz .LBB0_611
	v_lshl_add_u64 v[8:9], v[8:9], 2, s[6:7]
	global_load_dword v50, v[8:9], off
.LBB0_611:
	v_add_u32_e32 v8, 0x400, v34
	v_ashrrev_i32_e32 v38, 4, v8
	v_add_u32_e32 v12, s5, v38
	v_ashrrev_i32_e32 v13, 31, v12
	v_lshlrev_b64 v[8:9], 13, v[12:13]
	v_lshl_add_u64 v[8:9], v[28:29], 0, v[8:9]
	global_load_dwordx4 v[8:11], v[8:9], off
	s_and_b64 vcc, exec, s[0:1]
	s_cbranch_vccnz .LBB0_613
	v_lshl_add_u64 v[12:13], v[12:13], 2, s[6:7]
	global_load_dword v52, v[12:13], off
.LBB0_613:
	v_add_u32_e32 v12, 0x600, v34
	v_ashrrev_i32_e32 v39, 4, v12
	v_add_u32_e32 v16, s5, v39
	v_ashrrev_i32_e32 v17, 31, v16
	v_lshlrev_b64 v[12:13], 13, v[16:17]
	v_lshl_add_u64 v[12:13], v[28:29], 0, v[12:13]
	global_load_dwordx4 v[12:15], v[12:13], off
	s_and_b64 vcc, exec, s[0:1]
	s_cbranch_vccnz .LBB0_615
	v_lshl_add_u64 v[16:17], v[16:17], 2, s[6:7]
	global_load_dword v54, v[16:17], off
.LBB0_615:
	v_add_u32_e32 v16, 0x800, v34
	v_ashrrev_i32_e32 v40, 4, v16
	v_add_u32_e32 v20, s5, v40
	v_ashrrev_i32_e32 v21, 31, v20
	v_lshlrev_b64 v[16:17], 13, v[20:21]
	v_lshl_add_u64 v[16:17], v[28:29], 0, v[16:17]
	global_load_dwordx4 v[16:19], v[16:17], off
	s_and_b64 vcc, exec, s[0:1]
	s_cbranch_vccnz .LBB0_617
	v_lshl_add_u64 v[20:21], v[20:21], 2, s[6:7]
	global_load_dword v56, v[20:21], off
.LBB0_617:
	v_add_u32_e32 v20, 0xa00, v34
	v_ashrrev_i32_e32 v41, 4, v20
	v_add_u32_e32 v24, s5, v41
	v_ashrrev_i32_e32 v25, 31, v24
	v_lshlrev_b64 v[20:21], 13, v[24:25]
	v_lshl_add_u64 v[20:21], v[28:29], 0, v[20:21]
	global_load_dwordx4 v[20:23], v[20:21], off
	s_and_b64 vcc, exec, s[0:1]
	s_cbranch_vccnz .LBB0_619
	v_lshl_add_u64 v[24:25], v[24:25], 2, s[6:7]
	global_load_dword v58, v[24:25], off
.LBB0_619:
	v_add_u32_e32 v24, 0xc00, v34
	v_ashrrev_i32_e32 v42, 4, v24
	v_add_u32_e32 v30, s5, v42
	v_ashrrev_i32_e32 v31, 31, v30
	v_lshlrev_b64 v[24:25], 13, v[30:31]
	v_lshl_add_u64 v[24:25], v[28:29], 0, v[24:25]
	global_load_dwordx4 v[24:27], v[24:25], off
	s_and_b64 vcc, exec, s[0:1]
	s_cbranch_vccnz .LBB0_621
	v_lshl_add_u64 v[30:31], v[30:31], 2, s[6:7]
	global_load_dword v60, v[30:31], off
.LBB0_621:
	v_add_u32_e32 v30, 0xe00, v34
	v_ashrrev_i32_e32 v43, 4, v30
	v_add_u32_e32 v32, s5, v43
	v_ashrrev_i32_e32 v33, 31, v32
	v_lshlrev_b64 v[30:31], 13, v[32:33]
	v_lshl_add_u64 v[28:29], v[28:29], 0, v[30:31]
	global_load_dwordx4 v[28:31], v[28:29], off
	s_and_b64 vcc, exec, s[0:1]
	s_cbranch_vccnz .LBB0_623
	v_lshl_add_u64 v[32:33], v[32:33], 2, s[6:7]
	global_load_dword v62, v[32:33], off
	s_waitcnt vmcnt(0)
	v_pk_mul_f32 v[2:3], v[2:3], v[48:49] op_sel_hi:[1,0]
	v_pk_mul_f32 v[0:1], v[0:1], v[48:49] op_sel_hi:[1,0]
	v_pk_mul_f32 v[6:7], v[6:7], v[50:51] op_sel_hi:[1,0]
	v_pk_mul_f32 v[4:5], v[4:5], v[50:51] op_sel_hi:[1,0]
	v_pk_mul_f32 v[10:11], v[10:11], v[52:53] op_sel_hi:[1,0]
	v_pk_mul_f32 v[8:9], v[8:9], v[52:53] op_sel_hi:[1,0]
	v_pk_mul_f32 v[14:15], v[14:15], v[54:55] op_sel_hi:[1,0]
	v_pk_mul_f32 v[12:13], v[12:13], v[54:55] op_sel_hi:[1,0]
	v_pk_mul_f32 v[18:19], v[18:19], v[56:57] op_sel_hi:[1,0]
	v_pk_mul_f32 v[16:17], v[16:17], v[56:57] op_sel_hi:[1,0]
	v_pk_mul_f32 v[22:23], v[22:23], v[58:59] op_sel_hi:[1,0]
	v_pk_mul_f32 v[20:21], v[20:21], v[58:59] op_sel_hi:[1,0]
	v_pk_mul_f32 v[26:27], v[26:27], v[60:61] op_sel_hi:[1,0]
	v_pk_mul_f32 v[24:25], v[24:25], v[60:61] op_sel_hi:[1,0]
	v_pk_mul_f32 v[30:31], v[30:31], v[62:63] op_sel_hi:[1,0]
	v_pk_mul_f32 v[28:29], v[28:29], v[62:63] op_sel_hi:[1,0]

.LBB0_630:
	s_lshl_b32 s1, s9, 8
	s_and_b32 s4, s1, 0x300
	v_mov_b32_e32 v34, v194
	s_ashr_i32 s1, s0, 31
	s_lshl_b64 s[0:1], s[0:1], 2
	v_readlane_b32 s5, v235, 16
	v_lshlrev_b32_e32 v0, 2, v34
	v_ashrrev_i32_e32 v36, 4, v34
	s_add_u32 s0, s5, s0
	v_readlane_b32 s5, v235, 17
	v_and_b32_e32 v35, 60, v0
	v_add_u32_e32 v4, s4, v36
	s_addc_u32 s1, s5, s1
	v_lshlrev_b32_e32 v172, 2, v35
	v_ashrrev_i32_e32 v5, 31, v4
	v_lshl_add_u64 v[28:29], s[0:1], 0, v[172:173]
	v_lshlrev_b64 v[0:1], 15, v[4:5]
	v_lshl_add_u64 v[0:1], v[28:29], 0, v[0:1]
	s_barrier
	global_load_dwordx4 v[0:3], v[0:1], off
	v_readlane_b32 s6, v235, 18
	v_readlane_b32 s7, v235, 19
	s_andn2_b64 vcc, exec, s[6:7]
	s_nop 0
	v_cndmask_b32_e64 v6, 0, 1, s[6:7]
	v_cmp_ne_u32_e64 s[0:1], 1, v6
	s_cbranch_vccnz .LBB0_632
	v_lshl_add_u64 v[4:5], v[4:5], 2, s[52:53]
	global_load_dword v48, v[4:5], off
.LBB0_632:
	v_add_u32_e32 v4, 0x200, v34
	v_ashrrev_i32_e32 v37, 4, v4
	v_add_u32_e32 v8, s4, v37
	v_ashrrev_i32_e32 v9, 31, v8
	v_lshlrev_b64 v[4:5], 15, v[8:9]
	v_lshl_add_u64 v[4:5], v[28:29], 0, v[4:5]
	global_load_dwordx4 v[4:7], v[4:5], off
	s_and_b64 vcc, exec, s[0:1]
	s_cbranch_vccnz .LBB0_634
	v_lshl_add_u64 v[8:9], v[8:9], 2, s[52:53]
	global_load_dword v50, v[8:9], off
.LBB0_634:
	v_add_u32_e32 v8, 0x400, v34
	v_ashrrev_i32_e32 v38, 4, v8
	v_add_u32_e32 v12, s4, v38
	v_ashrrev_i32_e32 v13, 31, v12
	v_lshlrev_b64 v[8:9], 15, v[12:13]
	v_lshl_add_u64 v[8:9], v[28:29], 0, v[8:9]
	global_load_dwordx4 v[8:11], v[8:9], off
	s_and_b64 vcc, exec, s[0:1]
	s_cbranch_vccnz .LBB0_636
	v_lshl_add_u64 v[12:13], v[12:13], 2, s[52:53]
	global_load_dword v56, v[12:13], off
.LBB0_636:
	v_add_u32_e32 v12, 0x600, v34
	v_ashrrev_i32_e32 v39, 4, v12
	v_add_u32_e32 v16, s4, v39
	v_ashrrev_i32_e32 v17, 31, v16
	v_lshlrev_b64 v[12:13], 15, v[16:17]
	v_lshl_add_u64 v[12:13], v[28:29], 0, v[12:13]
	global_load_dwordx4 v[12:15], v[12:13], off
	s_and_b64 vcc, exec, s[0:1]
	s_cbranch_vccnz .LBB0_638
	v_lshl_add_u64 v[16:17], v[16:17], 2, s[52:53]
	global_load_dword v58, v[16:17], off
.LBB0_638:
	v_add_u32_e32 v16, 0x800, v34
	v_ashrrev_i32_e32 v40, 4, v16
	v_add_u32_e32 v20, s4, v40
	v_ashrrev_i32_e32 v21, 31, v20
	v_lshlrev_b64 v[16:17], 15, v[20:21]
	v_lshl_add_u64 v[16:17], v[28:29], 0, v[16:17]
	global_load_dwordx4 v[16:19], v[16:17], off
	s_and_b64 vcc, exec, s[0:1]
	s_cbranch_vccnz .LBB0_640
	v_lshl_add_u64 v[20:21], v[20:21], 2, s[52:53]
	global_load_dword v60, v[20:21], off
.LBB0_640:
	v_add_u32_e32 v20, 0xa00, v34
	v_ashrrev_i32_e32 v41, 4, v20
	v_add_u32_e32 v24, s4, v41
	v_ashrrev_i32_e32 v25, 31, v24
	v_lshlrev_b64 v[20:21], 15, v[24:25]
	v_lshl_add_u64 v[20:21], v[28:29], 0, v[20:21]
	global_load_dwordx4 v[20:23], v[20:21], off
	s_and_b64 vcc, exec, s[0:1]
	s_cbranch_vccnz .LBB0_642
	v_lshl_add_u64 v[24:25], v[24:25], 2, s[52:53]
	global_load_dword v62, v[24:25], off
.LBB0_642:
	v_add_u32_e32 v24, 0xc00, v34
	v_ashrrev_i32_e32 v42, 4, v24
	v_add_u32_e32 v30, s4, v42
	v_ashrrev_i32_e32 v31, 31, v30
	v_lshlrev_b64 v[24:25], 15, v[30:31]
	v_lshl_add_u64 v[24:25], v[28:29], 0, v[24:25]
	global_load_dwordx4 v[24:27], v[24:25], off
	s_and_b64 vcc, exec, s[0:1]
	s_cbranch_vccnz .LBB0_644
	v_lshl_add_u64 v[30:31], v[30:31], 2, s[52:53]
	global_load_dword v64, v[30:31], off
.LBB0_644:
	v_add_u32_e32 v30, 0xe00, v34
	v_ashrrev_i32_e32 v43, 4, v30
	v_add_u32_e32 v32, s4, v43
	v_ashrrev_i32_e32 v33, 31, v32
	v_lshlrev_b64 v[30:31], 15, v[32:33]
	v_lshl_add_u64 v[28:29], v[28:29], 0, v[30:31]
	global_load_dwordx4 v[28:31], v[28:29], off
	s_and_b64 vcc, exec, s[0:1]
	s_cbranch_vccnz .LBB0_596
	v_lshl_add_u64 v[32:33], v[32:33], 2, s[52:53]
	global_load_dword v66, v[32:33], off
	s_waitcnt vmcnt(0)
	v_pk_mul_f32 v[2:3], v[2:3], v[48:49] op_sel_hi:[1,0]
	v_pk_mul_f32 v[0:1], v[0:1], v[48:49] op_sel_hi:[1,0]
	v_pk_mul_f32 v[6:7], v[6:7], v[50:51] op_sel_hi:[1,0]
	v_pk_mul_f32 v[4:5], v[4:5], v[50:51] op_sel_hi:[1,0]
	v_pk_mul_f32 v[10:11], v[10:11], v[56:57] op_sel_hi:[1,0]
	v_pk_mul_f32 v[8:9], v[8:9], v[56:57] op_sel_hi:[1,0]
	v_pk_mul_f32 v[14:15], v[14:15], v[58:59] op_sel_hi:[1,0]
	v_pk_mul_f32 v[12:13], v[12:13], v[58:59] op_sel_hi:[1,0]
	v_pk_mul_f32 v[18:19], v[18:19], v[60:61] op_sel_hi:[1,0]
	v_pk_mul_f32 v[16:17], v[16:17], v[60:61] op_sel_hi:[1,0]
	v_pk_mul_f32 v[22:23], v[22:23], v[62:63] op_sel_hi:[1,0]
	v_pk_mul_f32 v[20:21], v[20:21], v[62:63] op_sel_hi:[1,0]
	v_pk_mul_f32 v[26:27], v[26:27], v[64:65] op_sel_hi:[1,0]
	v_pk_mul_f32 v[24:25], v[24:25], v[64:65] op_sel_hi:[1,0]
	v_pk_mul_f32 v[30:31], v[30:31], v[66:67] op_sel_hi:[1,0]
	v_pk_mul_f32 v[28:29], v[28:29], v[66:67] op_sel_hi:[1,0]
	s_branch .LBB0_596

.LBB0_737:
	s_or_b64 exec, exec, s[0:1]
	s_and_b64 s[0:1], s[78:79], exec
	v_readlane_b32 s0, v237, 57
	v_readlane_b32 s1, v237, 59
	s_cselect_b32 s36, s0, s1
	v_readlane_b32 s0, v237, 56
	v_readlane_b32 s1, v237, 58
	s_cselect_b32 s37, s0, s1
	v_readlane_b32 s0, v234, 48
	v_readlane_b32 s1, v234, 49
	s_mul_i32 s0, s0, 0x600000
	v_readlane_b32 s1, v237, 60
	v_readlane_b32 s4, v235, 58
	s_add_u32 s78, s1, s0
	v_readlane_b32 s0, v237, 61
	v_readlane_b32 s5, v235, 59
	s_addc_u32 s79, s0, 0
	s_mov_b64 s[0:1], -1
	s_and_b64 vcc, exec, s[4:5]
	s_waitcnt lgkmcnt(0)
	s_barrier
	s_cbranch_vccz .LBB0_823
	v_mov_b32_e32 v0, v194
	s_barrier
	s_nop 0
	v_readfirstlane_b32 s0, v0
	s_ashr_i32 s28, s0, 6
	v_readlane_b32 s0, v234, 57
	v_readlane_b32 s1, v234, 58
	s_and_b64 s[0:1], s[0:1], exec
	s_movk_i32 s0, 0x44
	s_cselect_b32 s46, 0x60, s0
	s_movk_i32 s47, 0xcc
	s_cselect_b32 s47, 0x180, s47
	v_readlane_b32 s0, v235, 62
	s_cmp_lt_u32 s0, s46
	s_cselect_b64 s[40:41], -1, 0
	s_cmp_ge_u32 s0, s46
	s_mov_b64 s[0:1], -1
	s_cbranch_scc0 .LBB0_765
	v_readlane_b32 s0, v234, 57
	v_readlane_b32 s1, v234, 58
	s_and_b64 s[0:1], s[0:1], exec
	s_movk_i32 s0, 0xffa0
	s_cselect_b32 s0, s0, 0xffffffbc
	v_readlane_b32 s1, v235, 62
	s_add_i32 s1, s0, s1
	s_add_i32 s52, s1, s47
	s_cmpk_gt_u32 s52, 0x3ff
	s_cbranch_scc1 .LBB0_764
	s_mul_i32 s1, s28, 0x2400
	v_readlane_b32 s4, v234, 48
	s_add_i32 s53, s1, 0
	s_mov_b32 s6, s4
	s_mul_i32 s1, s4, 0x98000
	v_readlane_b32 s4, v235, 2
	s_add_u32 s30, s4, s1
	v_readlane_b32 s1, v235, 3
	s_addc_u32 s31, s1, 0
	s_add_u32 s50, s30, 0x18000
	s_addc_u32 s51, s31, 0
	s_lshl_b32 s1, s6, 3
	s_or_b32 s29, s1, 0xffffff00
	s_add_u32 s34, s30, 0x58000
	s_addc_u32 s35, s31, 0
	s_lshl_b32 s1, s47, 3
	s_add_i32 s22, s2, s0
	s_add_i32 s1, s28, s1
	s_lshl_b32 s22, s22, 3
	s_add_i32 s1, s1, s22
	s_lshl_b32 s49, s0, 3
	s_lshl_b32 s20, s6, 10
	s_add_i32 s21, s0, 0xec
	s_add_i32 s48, s1, 0xffffff60
	s_addk_i32 s49, 0x760
	v_readlane_b32 s5, v234, 49
	s_branch .LBB0_742
